# v31 + static s_setprio 1 for waves 4-7 inside the three sample-attention tile loops (breaks the two-waves-per-SIMD lockstep), reset to 0 at loop exit
# speedup vs baseline: 1.0087x; 1.0087x over previous
.LBB0_227:
	s_or_b64 exec, exec, s[8:9]
	global_load_dwordx4 v[116:119], v[120:121], off offset:128
	v_mul_u32_u24_e32 v2, 0xd0, v132
	v_lshlrev_b32_e32 v122, 3, v18
	v_lshl_add_u32 v16, v18, 4, v2
	v_mul_u32_u24_e32 v2, 0x90, v132
	v_lshl_add_u32 v18, v19, 4, v0
	v_lshl_add_u64 v[124:125], v[12:13], 1, v[10:11]
	v_add_u32_e32 v0, 0xc0, v133
	s_movk_i32 s2, 0x300
	v_or_b32_e32 v17, v122, v2
	v_lshl_add_u64 v[126:127], v[14:15], 1, v[10:11]
	v_mad_i64_i32 v[128:129], s[8:9], v0, s2, v[124:125]
	v_add_u32_e32 v0, 0xc0, v134
	v_mov_b32_e32 v14, v1
	v_mov_b32_e32 v15, v1
	v_mad_i64_i32 v[130:131], s[8:9], v0, s2, v[126:127]
	v_mov_b32_e32 v0, v1
	v_mov_b32_e32 v2, v1
	v_mov_b32_e32 v3, v1
	v_mov_b32_e32 v4, v1
	v_mov_b32_e32 v5, v1
	v_mov_b32_e32 v6, v1
	v_mov_b32_e32 v7, v1
	v_mov_b32_e32 v8, v1
	v_mov_b32_e32 v9, v1
	v_mov_b32_e32 v10, v1
	v_mov_b32_e32 v11, v1
	v_mov_b32_e32 v12, v1
	v_mov_b32_e32 v13, v1
	v_add_u32_e32 v137, 0, v16
	v_add_u32_e32 v140, 0, v17
	v_add_u32_e32 v141, 0, v18
	v_mov_b64_e32 v[30:31], v[14:15]
	v_mov_b64_e32 v[46:47], v[14:15]
	v_ashrrev_i32_e32 v139, 31, v138
	v_mov_b32_e32 v142, 0xf149f2ca
	s_mov_b64 s[44:45], -1
	s_movk_i32 s2, 0x80
	v_mov_b32_e32 v143, 0
	v_mov_b64_e32 v[28:29], v[12:13]
	v_mov_b64_e32 v[26:27], v[10:11]
	v_mov_b64_e32 v[24:25], v[8:9]
	v_mov_b64_e32 v[22:23], v[6:7]
	v_mov_b64_e32 v[20:21], v[4:5]
	v_mov_b64_e32 v[18:19], v[2:3]
	v_mov_b64_e32 v[16:17], v[0:1]
	v_mov_b64_e32 v[44:45], v[12:13]
	v_mov_b64_e32 v[42:43], v[10:11]
	v_mov_b64_e32 v[40:41], v[8:9]
	v_mov_b64_e32 v[38:39], v[6:7]
	v_mov_b64_e32 v[36:37], v[4:5]
	v_mov_b64_e32 v[34:35], v[2:3]
	v_mov_b64_e32 v[32:33], v[0:1]
	s_waitcnt lgkmcnt(0)
	s_barrier
	v_cmp_lt_u32_e32 vcc, 0xff, v218
	s_nop 1
	s_cbranch_vccz .Lmy_np_229
	s_setprio 1
.Lmy_np_229:
	s_branch .LBB0_229
.LBB0_228:
	s_or_b64 exec, exec, s[8:9]
	v_add_f32_e32 v6, v11, v10
	v_add_f32_e32 v6, 0, v6
	v_add_f32_e32 v7, v13, v12
	v_add_f32_e32 v6, v7, v6
	v_add_f32_e32 v7, v15, v14
	v_add_f32_e32 v6, v7, v6
	v_add_f32_e32 v7, v49, v48
	v_add_f32_e32 v6, v7, v6
	v_add_f32_e32 v7, v51, v50
	v_add_f32_e32 v6, v7, v6
	v_add_f32_e32 v7, v53, v52
	v_add_f32_e32 v6, v7, v6
	v_add_f32_e32 v7, v64, v54
	v_add_f32_e32 v6, v7, v6
	v_add_f32_e32 v7, v65, v55
	v_add_f32_e32 v6, v7, v6
	v_add_f32_e32 v7, v66, v56
	v_add_f32_e32 v6, v7, v6
	v_add_f32_e32 v7, v67, v57
	v_add_f32_e32 v6, v7, v6
	v_add_f32_e32 v7, v68, v58
	v_add_f32_e32 v6, v7, v6
	v_add_f32_e32 v7, v69, v59
	v_add_f32_e32 v6, v7, v6
	v_add_f32_e32 v7, v70, v60
	v_add_f32_e32 v6, v7, v6
	v_add_f32_e32 v7, v71, v61
	v_add_f32_e32 v6, v7, v6
	v_add_f32_e32 v7, v72, v62
	s_waitcnt vmcnt(2)
	ds_write_b128 v136, v[2:5] offset:13312
	v_add_f32_e32 v6, v7, v6
	v_add_f32_e32 v7, v73, v63
	s_waitcnt lgkmcnt(0)
	s_barrier
	s_xor_b64 s[8:9], s[44:45], -1
	v_add_f32_e32 v6, v7, v6
	v_add_f32_e32 v143, v0, v6
	s_mov_b64 s[44:45], 0
	s_andn2_b64 vcc, exec, s[8:9]
	s_movk_i32 s2, 0xc0
	s_cbranch_vccz .LBB0_241

.LBB0_241:
	s_setprio 0
	v_cmp_lt_i32_e32 vcc, v232, v226
	v_lshlrev_b64 v[2:3], 11, v[138:139]
	s_nop 0
	v_cndmask_b32_e32 v0, v224, v232, vcc
	v_lshlrev_b32_e32 v0, 2, v0
	ds_bpermute_b32 v0, v0, v143
	s_waitcnt lgkmcnt(0)
	v_add_f32_e32 v4, v143, v0
	v_div_scale_f32 v5, s[8:9], v4, v4, 1.0
	v_rcp_f32_e32 v6, v5
	v_readlane_b32 s8, v253, 25
	v_readlane_b32 s9, v253, 26
	v_lshlrev_b32_e32 v0, 7, v123
	v_mov_b32_e32 v123, v1
	v_lshl_add_u64 v[2:3], s[8:9], 0, v[2:3]
	v_lshl_add_u64 v[2:3], v[2:3], 0, v[0:1]
	v_fma_f32 v0, -v5, v6, 1.0
	v_fmac_f32_e32 v6, v0, v6
	v_div_scale_f32 v0, vcc, 1.0, v4, 1.0
	v_mul_f32_e32 v7, v0, v6
	v_fma_f32 v8, -v5, v7, v0
	v_fmac_f32_e32 v7, v8, v6
	v_fma_f32 v0, -v5, v7, v0
	v_div_fmas_f32 v0, v0, v6, v7
	v_div_fixup_f32 v4, v0, v4, 1.0
	v_lshlrev_b32_e32 v0, 11, v132
	v_lshl_add_u64 v[2:3], v[2:3], 0, v[0:1]
	v_pk_mul_f32 v[6:7], v[32:33], v[4:5] op_sel_hi:[1,0]
	v_pk_mul_f32 v[8:9], v[34:35], v[4:5] op_sel_hi:[1,0]
	v_lshl_add_u64 v[2:3], v[2:3], 0, v[122:123]
	v_cvt_pk_bf16_f32 v6, v6, v7
	v_cvt_pk_bf16_f32 v7, v8, v9
	global_store_dwordx2 v[2:3], v[6:7], off offset:1536
	v_pk_mul_f32 v[6:7], v[36:37], v[4:5] op_sel_hi:[1,0]
	v_pk_mul_f32 v[8:9], v[38:39], v[4:5] op_sel_hi:[1,0]
	v_cvt_pk_bf16_f32 v6, v6, v7
	v_cvt_pk_bf16_f32 v7, v8, v9
	global_store_dwordx2 v[2:3], v[6:7], off offset:1552
	v_pk_mul_f32 v[6:7], v[40:41], v[4:5] op_sel_hi:[1,0]
	v_pk_mul_f32 v[8:9], v[42:43], v[4:5] op_sel_hi:[1,0]
	v_cvt_pk_bf16_f32 v6, v6, v7
	v_cvt_pk_bf16_f32 v7, v8, v9
	global_store_dwordx2 v[2:3], v[6:7], off offset:1568
	v_pk_mul_f32 v[6:7], v[44:45], v[4:5] op_sel_hi:[1,0]
	v_pk_mul_f32 v[8:9], v[46:47], v[4:5] op_sel_hi:[1,0]
	v_cvt_pk_bf16_f32 v6, v6, v7
	v_cvt_pk_bf16_f32 v7, v8, v9
	global_store_dwordx2 v[2:3], v[6:7], off offset:1584
	v_pk_mul_f32 v[6:7], v[16:17], v[4:5] op_sel_hi:[1,0]
	v_pk_mul_f32 v[8:9], v[18:19], v[4:5] op_sel_hi:[1,0]
	v_cvt_pk_bf16_f32 v6, v6, v7
	v_cvt_pk_bf16_f32 v7, v8, v9
	global_store_dwordx2 v[2:3], v[6:7], off offset:1600
	v_pk_mul_f32 v[6:7], v[20:21], v[4:5] op_sel_hi:[1,0]
	v_pk_mul_f32 v[8:9], v[22:23], v[4:5] op_sel_hi:[1,0]
	v_cvt_pk_bf16_f32 v6, v6, v7
	v_cvt_pk_bf16_f32 v7, v8, v9
	global_store_dwordx2 v[2:3], v[6:7], off offset:1616
	v_pk_mul_f32 v[6:7], v[24:25], v[4:5] op_sel_hi:[1,0]
	v_pk_mul_f32 v[8:9], v[26:27], v[4:5] op_sel_hi:[1,0]
	v_cvt_pk_bf16_f32 v6, v6, v7
	v_cvt_pk_bf16_f32 v7, v8, v9
	global_store_dwordx2 v[2:3], v[6:7], off offset:1632
	v_pk_mul_f32 v[6:7], v[28:29], v[4:5] op_sel_hi:[1,0]
	v_pk_mul_f32 v[4:5], v[30:31], v[4:5] op_sel_hi:[1,0]
	v_cvt_pk_bf16_f32 v6, v6, v7
	v_cvt_pk_bf16_f32 v7, v4, v5
	global_store_dwordx2 v[2:3], v[6:7], off offset:1648
.LBB0_242:
	s_andn2_saveexec_b64 s[38:39], s[42:43]
	s_cbranch_execz .LBB0_258
	v_readlane_b32 s8, v250, 33
	v_lshlrev_b32_e32 v0, 17, v6
	v_readlane_b32 s9, v250, 34
	v_lshlrev_b32_e32 v6, 7, v123
	v_mov_b32_e32 v7, v1
	v_lshl_add_u64 v[4:5], s[8:9], 0, v[0:1]
	v_readlane_b32 s8, v250, 35
	v_lshl_or_b32 v0, v123, 15, v0
	v_readlane_b32 s9, v250, 36
	v_ashrrev_i32_e32 v139, 31, v138
	v_lshl_add_u64 v[10:11], v[4:5], 0, v[6:7]
	v_lshl_add_u64 v[8:9], s[8:9], 0, v[0:1]
	v_readlane_b32 s8, v255, 29
	v_readlane_b32 s9, v255, 30
	v_lshlrev_b64 v[4:5], 9, v[138:139]
	v_and_b32_e32 v141, 31, v2
	v_lshlrev_b32_e32 v0, 9, v141
	v_mov_b32_e32 v20, v218
	v_mov_b32_e32 v21, v1
	global_load_dword v140, v1, s[8:9]
	v_readlane_b32 s8, v255, 31
	v_readlane_b32 s9, v255, 32
	v_lshlrev_b32_e32 v144, 6, v123
	s_mov_b64 s[10:11], -1
	s_movk_i32 s2, 0x80
	v_mov_b32_e32 v158, 0xf149f2ca
	v_mov_b32_e32 v157, 0
	global_load_dword v143, v1, s[8:9]
	v_readlane_b32 s8, v250, 37
	v_readlane_b32 s9, v250, 38
	v_mov_b32_e32 v156, 0
	v_ashrrev_i32_e32 v12, 3, v20
	v_lshl_add_u64 v[4:5], s[8:9], 0, v[4:5]
	v_lshl_add_u64 v[4:5], v[4:5], 0, v[6:7]
	v_lshrrev_b32_e32 v6, 5, v3
	v_lshl_add_u64 v[2:3], v[4:5], 0, v[0:1]
	v_lshlrev_b32_e32 v0, 4, v6
	v_lshl_add_u64 v[2:3], v[2:3], 0, v[0:1]
	global_load_dwordx4 v[82:85], v[2:3], off
	global_load_dwordx4 v[86:89], v[2:3], off offset:32
	global_load_dwordx4 v[90:93], v[2:3], off offset:64
	global_load_dwordx4 v[94:97], v[2:3], off offset:96
	v_ashrrev_i32_e32 v2, 31, v20
	v_lshrrev_b32_e32 v2, 29, v2
	v_add_u32_e32 v2, v20, v2
	v_ashrrev_i32_e32 v146, 3, v2
	v_and_b32_e32 v2, -8, v2
	v_sub_u32_e32 v22, v20, v2
	v_ashrrev_i32_e32 v147, 31, v146
	v_lshlrev_b32_e32 v4, 3, v22
	v_lshlrev_b64 v[14:15], 9, v[146:147]
	v_ashrrev_i32_e32 v5, 31, v4
	v_ashrrev_i32_e32 v13, 31, v12
	v_lshlrev_b32_e32 v142, 3, v6
	v_lshl_add_u64 v[2:3], v[10:11], 0, v[14:15]
	v_lshlrev_b64 v[16:17], 1, v[4:5]
	v_lshlrev_b64 v[6:7], 9, v[12:13]
	v_lshl_add_u64 v[18:19], v[2:3], 0, v[16:17]
	v_lshl_add_u64 v[6:7], v[8:9], 0, v[6:7]
	v_lshlrev_b32_e32 v8, 4, v20
	global_load_dwordx4 v[2:5], v[18:19], off
	v_and_b32_e32 v20, 0x70, v8
	v_lshl_add_u64 v[148:149], v[6:7], 0, v[20:21]
	global_load_dwordx4 v[6:9], v[148:149], off
	v_mul_lo_u32 v13, v146, s46
	v_lshl_add_u32 v13, v22, 4, v13
	v_add_u32_e32 v145, 0, v13
	v_add_u32_e32 v154, 0, v0
	v_lshl_add_u64 v[150:151], v[10:11], 0, v[16:17]
	v_mov_b32_e32 v16, v1
	v_mov_b32_e32 v17, v1
	v_mov_b32_e32 v10, v1
	v_mov_b32_e32 v11, v1
	v_mov_b32_e32 v13, v1
	v_mov_b32_e32 v159, 0xf149f2ca
	s_waitcnt vmcnt(1)
	ds_write_b128 v145, v[2:5]
	v_mad_u64_u32 v[2:3], s[8:9], v12, s46, v[20:21]
	v_add_u32_e32 v147, 0, v2
	v_add_co_u32_e32 v2, vcc, s62, v18
	s_waitcnt vmcnt(0)
	ds_write_b128 v147, v[6:9] offset:9216
	v_addc_co_u32_e32 v3, vcc, 0, v19, vcc
	global_load_dwordx4 v[98:101], v[2:3], off
	global_load_dwordx4 v[102:105], v[148:149], off offset:128
	v_sub_u32_e32 v4, v154, v142
	v_lshl_add_u64 v[2:3], v[150:151], 0, v[14:15]
	s_mov_b64 s[8:9], 0x18000
	v_lshl_add_u64 v[152:153], v[2:3], 0, s[8:9]
	v_mad_u32_u24 v155, v141, s46, v4
	v_mov_b32_e32 v2, v1
	v_mov_b32_e32 v3, v1
	v_mov_b32_e32 v4, v1
	v_mov_b32_e32 v5, v1
	v_mov_b32_e32 v6, v1
	v_mov_b32_e32 v7, v1
	v_mov_b32_e32 v8, v1
	v_mov_b32_e32 v9, v1
	v_mov_b32_e32 v12, v1
	v_mov_b32_e32 v14, v1
	v_mov_b32_e32 v15, v1
	v_mov_b64_e32 v[32:33], v[16:17]
	v_mov_b64_e32 v[64:65], v[16:17]
	v_mov_b64_e32 v[48:49], v[16:17]
	v_mov_b64_e32 v[30:31], v[14:15]
	v_mov_b64_e32 v[28:29], v[12:13]
	v_mov_b64_e32 v[26:27], v[10:11]
	v_mov_b64_e32 v[24:25], v[8:9]
	v_mov_b64_e32 v[22:23], v[6:7]
	v_mov_b64_e32 v[20:21], v[4:5]
	v_mov_b64_e32 v[18:19], v[2:3]
	v_mov_b64_e32 v[62:63], v[14:15]
	v_mov_b64_e32 v[60:61], v[12:13]
	v_mov_b64_e32 v[58:59], v[10:11]
	v_mov_b64_e32 v[56:57], v[8:9]
	v_mov_b64_e32 v[54:55], v[6:7]
	v_mov_b64_e32 v[52:53], v[4:5]
	v_mov_b64_e32 v[50:51], v[2:3]
	v_mov_b64_e32 v[46:47], v[14:15]
	v_mov_b64_e32 v[44:45], v[12:13]
	v_mov_b64_e32 v[42:43], v[10:11]
	v_mov_b64_e32 v[40:41], v[8:9]
	v_mov_b64_e32 v[38:39], v[6:7]
	v_mov_b64_e32 v[36:37], v[4:5]
	v_mov_b64_e32 v[34:35], v[2:3]
	s_waitcnt lgkmcnt(0)
	s_barrier
	v_cmp_lt_u32_e32 vcc, 0xff, v218
	s_nop 1
	s_cbranch_vccz .Lmy_np_245
	s_setprio 1
.Lmy_np_245:
	s_branch .LBB0_245
.LBB0_244:
	s_waitcnt vmcnt(3)
	ds_write_b128 v145, v[106:109]
	s_waitcnt vmcnt(2)
	ds_write_b128 v147, v[110:113] offset:9216
	s_waitcnt lgkmcnt(0)
	s_barrier
	s_andn2_b64 vcc, exec, s[8:9]
	s_movk_i32 s2, 0xc0
	s_cbranch_vccz .LBB0_257

.LBB0_257:
	s_setprio 0
	v_readlane_b32 s8, v253, 25
	v_lshlrev_b64 v[66:67], 11, v[138:139]
	v_readlane_b32 s9, v253, 26
	v_lshlrev_b32_e32 v68, 1, v144
	v_mov_b32_e32 v69, v1
	v_lshl_add_u64 v[66:67], s[8:9], 0, v[66:67]
	v_cmp_lt_i32_e32 vcc, v232, v226
	v_lshl_add_u64 v[66:67], v[66:67], 0, v[68:69]
	v_pk_mul_f32 v[46:47], v[140:141], v[46:47] op_sel_hi:[0,1]
	v_cndmask_b32_e32 v68, v224, v232, vcc
	v_lshlrev_b32_e32 v73, 2, v68
	ds_bpermute_b32 v68, v73, v157
	v_sub_f32_e32 v71, 1.0, v143
	v_pk_mul_f32 v[50:51], v[140:141], v[50:51] op_sel_hi:[0,1]
	v_pk_mul_f32 v[52:53], v[140:141], v[52:53] op_sel_hi:[0,1]
	v_mov_b32_e32 v143, v1
	s_waitcnt lgkmcnt(0)
	v_add_f32_e32 v68, v157, v68
	v_div_scale_f32 v69, s[8:9], v68, v68, 1.0
	v_rcp_f32_e32 v70, v69
	v_pk_mul_f32 v[54:55], v[140:141], v[54:55] op_sel_hi:[0,1]
	v_pk_mul_f32 v[58:59], v[140:141], v[58:59] op_sel_hi:[0,1]
	v_pk_mul_f32 v[62:63], v[140:141], v[62:63] op_sel_hi:[0,1]
	v_fma_f32 v72, -v69, v70, 1.0
	v_fmac_f32_e32 v70, v72, v70
	v_div_scale_f32 v72, vcc, 1.0, v68, 1.0
	v_mul_f32_e32 v74, v72, v70
	v_fma_f32 v75, -v69, v74, v72
	v_fmac_f32_e32 v74, v75, v70
	v_fma_f32 v69, -v69, v74, v72
	v_div_fmas_f32 v69, v69, v70, v74
	v_div_fixup_f32 v70, v69, v68, 1.0
	ds_bpermute_b32 v68, v73, v156
	v_pk_mul_f32 v[34:35], v[140:141], v[34:35] op_sel_hi:[0,1]
	v_pk_mul_f32 v[36:37], v[140:141], v[36:37] op_sel_hi:[0,1]
	v_pk_mul_f32 v[38:39], v[140:141], v[38:39] op_sel_hi:[0,1]
	v_pk_mul_f32 v[40:41], v[140:141], v[40:41] op_sel_hi:[0,1]
	s_waitcnt lgkmcnt(0)
	v_add_f32_e32 v68, v156, v68
	v_div_scale_f32 v69, s[8:9], v68, v68, 1.0
	v_rcp_f32_e32 v72, v69
	v_readlane_b32 s8, v255, 33
	v_readlane_b32 s9, v255, 34
	v_pk_mul_f32 v[42:43], v[140:141], v[42:43] op_sel_hi:[0,1]
	v_fma_f32 v74, -v69, v72, 1.0
	v_fmac_f32_e32 v72, v74, v72
	v_div_scale_f32 v74, vcc, 1.0, v68, 1.0
	v_mul_f32_e32 v75, v74, v72
	v_fma_f32 v76, -v69, v75, v74
	v_fmac_f32_e32 v75, v76, v72
	v_fma_f32 v69, -v69, v75, v74
	v_div_fmas_f32 v69, v69, v72, v75
	v_div_fixup_f32 v72, v69, v68, 1.0
	v_lshlrev_b32_e32 v68, 11, v141
	v_mov_b32_e32 v69, v1
	v_pk_mul_f32 v[46:47], v[46:47], v[72:73] op_sel_hi:[1,0]
	v_pk_mul_f32 v[50:51], v[50:51], v[72:73] op_sel_hi:[1,0]
	v_pk_fma_f32 v[46:47], v[30:31], v[70:71], v[46:47] op_sel_hi:[1,0,1] neg_lo:[0,0,1] neg_hi:[0,0,1]
	v_pk_mul_f32 v[30:31], v[140:141], v[48:49] op_sel_hi:[0,1]
	v_lshl_add_u64 v[48:49], v[66:67], 0, v[68:69]
	global_load_dwordx4 v[66:69], v0, s[8:9]
	v_pk_mul_f32 v[52:53], v[52:53], v[72:73] op_sel_hi:[1,0]
	v_pk_fma_f32 v[50:51], v[2:3], v[70:71], v[50:51] op_sel_hi:[1,0,1] neg_lo:[0,0,1] neg_hi:[0,0,1]
	v_pk_fma_f32 v[4:5], v[4:5], v[70:71], v[52:53] op_sel_hi:[1,0,1] neg_lo:[0,0,1] neg_hi:[0,0,1]
	v_pk_mul_f32 v[76:77], v[50:51], v[50:51]
	v_pk_mul_f32 v[52:53], v[4:5], v[4:5]
	v_lshl_add_u64 v[2:3], v[48:49], 0, v[142:143]
	v_pk_mul_f32 v[48:49], v[140:141], v[56:57] op_sel_hi:[0,1]
	v_pk_mul_f32 v[54:55], v[54:55], v[72:73] op_sel_hi:[1,0]
	v_pk_mul_f32 v[56:57], v[140:141], v[60:61] op_sel_hi:[0,1]
	v_pk_mul_f32 v[60:61], v[140:141], v[64:65] op_sel_hi:[0,1]
	v_add_f32_e32 v64, v76, v77
	v_pk_fma_f32 v[54:55], v[6:7], v[70:71], v[54:55] op_sel_hi:[1,0,1] neg_lo:[0,0,1] neg_hi:[0,0,1]
	v_add_f32_e32 v52, v52, v64
	v_pk_mul_f32 v[48:49], v[48:49], v[72:73] op_sel_hi:[1,0]
	v_pk_mul_f32 v[6:7], v[54:55], v[54:55]
	v_add_f32_e32 v52, v53, v52
	v_pk_fma_f32 v[8:9], v[8:9], v[70:71], v[48:49] op_sel_hi:[1,0,1] neg_lo:[0,0,1] neg_hi:[0,0,1]
	v_add_f32_e32 v6, v6, v52
	v_pk_mul_f32 v[48:49], v[8:9], v[8:9]
	v_pk_mul_f32 v[58:59], v[58:59], v[72:73] op_sel_hi:[1,0]
	v_add_f32_e32 v6, v7, v6
	v_pk_fma_f32 v[10:11], v[10:11], v[70:71], v[58:59] op_sel_hi:[1,0,1] neg_lo:[0,0,1] neg_hi:[0,0,1]
	v_add_f32_e32 v6, v48, v6
	v_pk_mul_f32 v[56:57], v[56:57], v[72:73] op_sel_hi:[1,0]
	v_pk_mul_f32 v[58:59], v[10:11], v[10:11]
	v_add_f32_e32 v6, v49, v6
	v_pk_fma_f32 v[12:13], v[12:13], v[70:71], v[56:57] op_sel_hi:[1,0,1] neg_lo:[0,0,1] neg_hi:[0,0,1]
	v_add_f32_e32 v6, v58, v6
	v_pk_mul_f32 v[56:57], v[12:13], v[12:13]
	v_pk_mul_f32 v[62:63], v[62:63], v[72:73] op_sel_hi:[1,0]
	v_add_f32_e32 v6, v59, v6
	v_pk_fma_f32 v[14:15], v[14:15], v[70:71], v[62:63] op_sel_hi:[1,0,1] neg_lo:[0,0,1] neg_hi:[0,0,1]
	v_add_f32_e32 v6, v56, v6
	v_pk_mul_f32 v[60:61], v[60:61], v[72:73] op_sel_hi:[1,0]
	v_pk_mul_f32 v[62:63], v[14:15], v[14:15]
	v_add_f32_e32 v6, v57, v6
	v_pk_fma_f32 v[16:17], v[16:17], v[70:71], v[60:61] op_sel_hi:[1,0,1] neg_lo:[0,0,1] neg_hi:[0,0,1]
	v_add_f32_e32 v6, v62, v6
	v_pk_mul_f32 v[60:61], v[16:17], v[16:17]
	v_pk_mul_f32 v[34:35], v[34:35], v[72:73] op_sel_hi:[1,0]
	v_add_f32_e32 v6, v63, v6
	v_pk_fma_f32 v[18:19], v[18:19], v[70:71], v[34:35] op_sel_hi:[1,0,1] neg_lo:[0,0,1] neg_hi:[0,0,1]
	v_add_f32_e32 v6, v60, v6
	v_pk_mul_f32 v[36:37], v[36:37], v[72:73] op_sel_hi:[1,0]
	v_pk_mul_f32 v[34:35], v[18:19], v[18:19]
	v_add_f32_e32 v6, v61, v6
	v_pk_fma_f32 v[20:21], v[20:21], v[70:71], v[36:37] op_sel_hi:[1,0,1] neg_lo:[0,0,1] neg_hi:[0,0,1]
	v_add_f32_e32 v6, v34, v6
	v_pk_mul_f32 v[36:37], v[20:21], v[20:21]
	v_pk_mul_f32 v[38:39], v[38:39], v[72:73] op_sel_hi:[1,0]
	v_add_f32_e32 v6, v35, v6
	v_pk_fma_f32 v[22:23], v[22:23], v[70:71], v[38:39] op_sel_hi:[1,0,1] neg_lo:[0,0,1] neg_hi:[0,0,1]
	v_add_f32_e32 v6, v36, v6
	v_pk_mul_f32 v[40:41], v[40:41], v[72:73] op_sel_hi:[1,0]
	v_pk_mul_f32 v[38:39], v[22:23], v[22:23]
	v_add_f32_e32 v6, v37, v6
	v_pk_fma_f32 v[24:25], v[24:25], v[70:71], v[40:41] op_sel_hi:[1,0,1] neg_lo:[0,0,1] neg_hi:[0,0,1]
	v_add_f32_e32 v6, v38, v6
	v_pk_mul_f32 v[40:41], v[24:25], v[24:25]
	v_pk_mul_f32 v[42:43], v[42:43], v[72:73] op_sel_hi:[1,0]
	v_add_f32_e32 v6, v39, v6
	v_pk_mul_f32 v[44:45], v[140:141], v[44:45] op_sel_hi:[0,1]
	v_pk_fma_f32 v[26:27], v[26:27], v[70:71], v[42:43] op_sel_hi:[1,0,1] neg_lo:[0,0,1] neg_hi:[0,0,1]
	v_add_f32_e32 v6, v40, v6
	v_pk_mul_f32 v[44:45], v[44:45], v[72:73] op_sel_hi:[1,0]
	v_pk_mul_f32 v[42:43], v[26:27], v[26:27]
	v_add_f32_e32 v6, v41, v6
	v_pk_fma_f32 v[28:29], v[28:29], v[70:71], v[44:45] op_sel_hi:[1,0,1] neg_lo:[0,0,1] neg_hi:[0,0,1]
	v_add_f32_e32 v6, v42, v6
	v_pk_mul_f32 v[44:45], v[28:29], v[28:29]
	v_add_f32_e32 v6, v43, v6
	v_add_f32_e32 v6, v44, v6
	v_pk_mul_f32 v[74:75], v[46:47], v[46:47]
	v_pk_mul_f32 v[30:31], v[30:31], v[72:73] op_sel_hi:[1,0]
	v_add_f32_e32 v6, v45, v6
	v_pk_fma_f32 v[30:31], v[32:33], v[70:71], v[30:31] op_sel_hi:[1,0,1] neg_lo:[0,0,1] neg_hi:[0,0,1]
	v_add_f32_e32 v6, v74, v6
	v_pk_mul_f32 v[32:33], v[30:31], v[30:31]
	v_add_f32_e32 v6, v75, v6
	v_add_f32_e32 v6, v32, v6
	v_add_f32_e32 v6, v33, v6
	ds_bpermute_b32 v7, v73, v6
	s_waitcnt lgkmcnt(0)
	v_add_f32_e32 v6, v6, v7
	v_fmamk_f32 v6, v6, 0x3c800000, v219
	v_cmp_gt_f32_e32 vcc, s33, v6
	v_mul_f32_e32 v7, 0x4b800000, v6
	s_nop 0
	v_cndmask_b32_e32 v6, v6, v7, vcc
	v_rsq_f32_e32 v6, v6
	s_nop 0
	v_mul_f32_e32 v7, 0x45800000, v6
	v_cndmask_b32_e32 v6, v6, v7, vcc
	v_mul_f32_e32 v32, v71, v6
	v_pk_mul_f32 v[6:7], v[50:51], v[32:33] op_sel_hi:[1,0]
	v_pk_mul_f32 v[4:5], v[4:5], v[32:33] op_sel_hi:[1,0]
	s_waitcnt vmcnt(0)
	v_pk_mul_f32 v[6:7], v[66:67], v[6:7]
	v_pk_mul_f32 v[4:5], v[68:69], v[4:5]
	v_cvt_pk_bf16_f32 v6, v6, v7
	v_cvt_pk_bf16_f32 v7, v4, v5
	global_store_dwordx2 v[2:3], v[6:7], off offset:1024
	global_load_dwordx4 v[4:7], v0, s[8:9] offset:32
	v_pk_mul_f32 v[34:35], v[54:55], v[32:33] op_sel_hi:[1,0]
	v_pk_mul_f32 v[8:9], v[8:9], v[32:33] op_sel_hi:[1,0]
	s_waitcnt vmcnt(0)
	v_pk_mul_f32 v[4:5], v[4:5], v[34:35]
	v_pk_mul_f32 v[6:7], v[6:7], v[8:9]
	v_cvt_pk_bf16_f32 v4, v4, v5
	v_cvt_pk_bf16_f32 v5, v6, v7
	global_store_dwordx2 v[2:3], v[4:5], off offset:1040
	global_load_dwordx4 v[4:7], v0, s[8:9] offset:64
	v_pk_mul_f32 v[8:9], v[10:11], v[32:33] op_sel_hi:[1,0]
	s_waitcnt vmcnt(0)
	v_pk_mul_f32 v[4:5], v[4:5], v[8:9]
	v_pk_mul_f32 v[8:9], v[12:13], v[32:33] op_sel_hi:[1,0]
	v_cvt_pk_bf16_f32 v4, v4, v5
	v_pk_mul_f32 v[6:7], v[6:7], v[8:9]
	v_pk_mul_f32 v[8:9], v[14:15], v[32:33] op_sel_hi:[1,0]
	v_cvt_pk_bf16_f32 v5, v6, v7
	global_store_dwordx2 v[2:3], v[4:5], off offset:1056
	global_load_dwordx4 v[4:7], v0, s[8:9] offset:96
	s_waitcnt vmcnt(0)
	v_pk_mul_f32 v[4:5], v[4:5], v[8:9]
	v_pk_mul_f32 v[8:9], v[16:17], v[32:33] op_sel_hi:[1,0]
	v_cvt_pk_bf16_f32 v4, v4, v5
	v_pk_mul_f32 v[6:7], v[6:7], v[8:9]
	v_pk_mul_f32 v[8:9], v[18:19], v[32:33] op_sel_hi:[1,0]
	v_cvt_pk_bf16_f32 v5, v6, v7
	global_store_dwordx2 v[2:3], v[4:5], off offset:1072
	global_load_dwordx4 v[4:7], v0, s[8:9] offset:128
	s_waitcnt vmcnt(0)
	v_pk_mul_f32 v[4:5], v[4:5], v[8:9]
	v_pk_mul_f32 v[8:9], v[20:21], v[32:33] op_sel_hi:[1,0]
	v_cvt_pk_bf16_f32 v4, v4, v5
	v_pk_mul_f32 v[6:7], v[6:7], v[8:9]
	v_pk_mul_f32 v[8:9], v[22:23], v[32:33] op_sel_hi:[1,0]
	v_cvt_pk_bf16_f32 v5, v6, v7
	global_store_dwordx2 v[2:3], v[4:5], off offset:1088
	global_load_dwordx4 v[4:7], v0, s[8:9] offset:160
	s_waitcnt vmcnt(0)
	v_pk_mul_f32 v[4:5], v[4:5], v[8:9]
	v_pk_mul_f32 v[8:9], v[24:25], v[32:33] op_sel_hi:[1,0]
	v_cvt_pk_bf16_f32 v4, v4, v5
	v_pk_mul_f32 v[6:7], v[6:7], v[8:9]
	v_pk_mul_f32 v[8:9], v[26:27], v[32:33] op_sel_hi:[1,0]
	v_cvt_pk_bf16_f32 v5, v6, v7
	global_store_dwordx2 v[2:3], v[4:5], off offset:1104
	global_load_dwordx4 v[4:7], v0, s[8:9] offset:192
	s_waitcnt vmcnt(0)
	v_pk_mul_f32 v[4:5], v[4:5], v[8:9]
	v_pk_mul_f32 v[8:9], v[28:29], v[32:33] op_sel_hi:[1,0]
	v_cvt_pk_bf16_f32 v4, v4, v5
	v_pk_mul_f32 v[6:7], v[6:7], v[8:9]
	v_pk_mul_f32 v[8:9], v[46:47], v[32:33] op_sel_hi:[1,0]
	v_cvt_pk_bf16_f32 v5, v6, v7
	global_store_dwordx2 v[2:3], v[4:5], off offset:1120
	global_load_dwordx4 v[4:7], v0, s[8:9] offset:224
	s_waitcnt vmcnt(0)
	v_pk_mul_f32 v[4:5], v[4:5], v[8:9]
	v_pk_mul_f32 v[8:9], v[30:31], v[32:33] op_sel_hi:[1,0]
	v_cvt_pk_bf16_f32 v4, v4, v5
	v_pk_mul_f32 v[6:7], v[6:7], v[8:9]
	s_nop 0
	v_cvt_pk_bf16_f32 v5, v6, v7
	global_store_dwordx2 v[2:3], v[4:5], off offset:1136

.LBB0_259:
	s_andn2_saveexec_b64 s[38:39], s[40:41]
	s_cbranch_execz .LBB0_267
	v_readlane_b32 s8, v250, 39
	v_lshlrev_b32_e32 v0, 16, v6
	v_readlane_b32 s9, v250, 40
	v_lshrrev_b32_e32 v8, 1, v123
	v_lshlrev_b32_e32 v6, 7, v8
	v_lshl_add_u64 v[4:5], s[8:9], 0, v[0:1]
	v_readlane_b32 s8, v250, 41
	v_mov_b32_e32 v7, v1
	v_lshl_or_b32 v0, v8, 15, v0
	v_readlane_b32 s9, v250, 42
	v_lshl_add_u64 v[10:11], v[4:5], 0, v[6:7]
	v_ashrrev_i32_e32 v139, 31, v138
	v_lshl_add_u64 v[6:7], s[8:9], 0, v[0:1]
	v_readlane_b32 s8, v252, 59
	v_lshlrev_b64 v[4:5], 9, v[138:139]
	v_readlane_b32 s9, v252, 60
	v_lshlrev_b32_e32 v0, 7, v123
	v_and_b32_e32 v105, 31, v2
	v_lshl_add_u64 v[4:5], s[8:9], 0, v[4:5]
	v_lshl_add_u64 v[4:5], v[4:5], 0, v[0:1]
	v_lshrrev_b32_e32 v8, 5, v3
	v_lshlrev_b32_e32 v0, 9, v105
	v_lshl_add_u64 v[2:3], v[4:5], 0, v[0:1]
	v_lshlrev_b32_e32 v0, 4, v8
	v_mov_b32_e32 v20, v218
	v_lshl_add_u64 v[2:3], v[2:3], 0, v[0:1]
	global_load_dwordx4 v[80:83], v[2:3], off
	global_load_dwordx4 v[84:87], v[2:3], off offset:32
	global_load_dwordx4 v[88:91], v[2:3], off offset:64
	global_load_dwordx4 v[92:95], v[2:3], off offset:96
	v_ashrrev_i32_e32 v2, 31, v20
	v_lshrrev_b32_e32 v2, 29, v2
	v_add_u32_e32 v2, v20, v2
	s_waitcnt vmcnt(13)
	v_ashrrev_i32_e32 v108, 3, v2
	v_and_b32_e32 v2, -8, v2
	v_sub_u32_e32 v22, v20, v2
	v_ashrrev_i32_e32 v12, 3, v20
	v_ashrrev_i32_e32 v109, 31, v108
	v_lshlrev_b32_e32 v4, 3, v22
	v_lshlrev_b64 v[14:15], 8, v[108:109]
	v_ashrrev_i32_e32 v5, 31, v4
	v_ashrrev_i32_e32 v13, 31, v12
	v_lshlrev_b32_e32 v104, 3, v8
	v_lshl_add_u64 v[2:3], v[10:11], 0, v[14:15]
	v_lshlrev_b64 v[16:17], 1, v[4:5]
	v_lshlrev_b64 v[8:9], 9, v[12:13]
	v_lshl_add_u64 v[18:19], v[2:3], 0, v[16:17]
	v_lshl_add_u64 v[6:7], v[6:7], 0, v[8:9]
	v_lshlrev_b32_e32 v8, 4, v20
	global_load_dwordx4 v[2:5], v[18:19], off
	v_and_b32_e32 v20, 0x70, v8
	v_mov_b32_e32 v21, v1
	v_lshl_add_u64 v[110:111], v[6:7], 0, v[20:21]
	global_load_dwordx4 v[6:9], v[110:111], off
	v_mul_lo_u32 v13, v108, s46
	v_lshl_add_u32 v13, v22, 4, v13
	v_add_u32_e32 v107, 0, v13
	s_movk_i32 s2, 0x4000
	s_waitcnt vmcnt(14)
	v_mad_u32_u24 v116, v105, s46, v0
	v_lshl_add_u64 v[112:113], v[10:11], 0, v[16:17]
	v_mov_b32_e32 v0, v1
	v_mov_b32_e32 v10, v1
	v_mov_b32_e32 v11, v1
	v_mov_b32_e32 v13, v1
	v_lshlrev_b32_e32 v106, 6, v123
	v_mov_b32_e32 v119, 0xf149f2ca
	v_mov_b32_e32 v121, 0
	s_waitcnt vmcnt(1)
	ds_write_b128 v107, v[2:5]
	v_mad_u64_u32 v[2:3], s[8:9], v12, s46, v[20:21]
	v_add_u32_e32 v109, 0, v2
	v_add_co_u32_e32 v2, vcc, s2, v18
	s_waitcnt vmcnt(0)
	ds_write_b128 v109, v[6:9] offset:9216
	v_addc_co_u32_e32 v3, vcc, 0, v19, vcc
	global_load_dwordx4 v[96:99], v[2:3], off
	global_load_dwordx4 v[100:103], v[110:111], off offset:128
	v_mul_u32_u24_e32 v2, 0x90, v105
	v_or_b32_e32 v18, v104, v2
	v_sub_u32_e32 v19, v116, v104
	v_lshl_add_u64 v[2:3], v[112:113], 0, v[14:15]
	s_mov_b64 s[8:9], 0xc000
	v_mov_b32_e32 v14, v1
	v_mov_b32_e32 v15, v1
	v_lshl_add_u64 v[114:115], v[2:3], 0, s[8:9]
	v_mov_b32_e32 v2, v1
	v_mov_b32_e32 v3, v1
	v_mov_b32_e32 v4, v1
	v_mov_b32_e32 v5, v1
	v_mov_b32_e32 v6, v1
	v_mov_b32_e32 v7, v1
	v_mov_b32_e32 v8, v1
	v_mov_b32_e32 v9, v1
	v_mov_b32_e32 v12, v1
	v_add_u32_e32 v117, 0, v18
	v_add_u32_e32 v118, 0, v19
	v_mov_b64_e32 v[30:31], v[14:15]
	v_mov_b64_e32 v[46:47], v[14:15]
	s_mov_b64 s[8:9], -1
	s_movk_i32 s2, 0x80
	v_mov_b64_e32 v[28:29], v[12:13]
	v_mov_b64_e32 v[26:27], v[10:11]
	v_mov_b64_e32 v[24:25], v[8:9]
	v_mov_b64_e32 v[22:23], v[6:7]
	v_mov_b64_e32 v[20:21], v[4:5]
	v_mov_b64_e32 v[18:19], v[2:3]
	v_mov_b64_e32 v[16:17], v[0:1]
	v_mov_b64_e32 v[44:45], v[12:13]
	v_mov_b64_e32 v[42:43], v[10:11]
	v_mov_b64_e32 v[40:41], v[8:9]
	v_mov_b64_e32 v[38:39], v[6:7]
	v_mov_b64_e32 v[36:37], v[4:5]
	v_mov_b64_e32 v[34:35], v[2:3]
	v_mov_b64_e32 v[32:33], v[0:1]
	s_waitcnt lgkmcnt(0)
	s_barrier
	v_cmp_lt_u32_e32 vcc, 0xff, v218
	s_nop 1
	s_cbranch_vccz .Lmy_np_262
	s_setprio 1
.Lmy_np_262:
	s_branch .LBB0_262
.LBB0_261:
	v_sub_f32_e32 v13, v65, v119
	v_sub_f32_e32 v14, v67, v119
	v_sub_f32_e32 v0, v64, v119
	v_sub_f32_e32 v10, v48, v119
	v_exp_f32_e32 v48, v13
	v_sub_f32_e32 v13, v49, v119
	v_exp_f32_e32 v124, v14
	v_sub_f32_e32 v14, v51, v119
	v_exp_f32_e32 v0, v0
	v_exp_f32_e32 v10, v10
	v_exp_f32_e32 v122, v13
	v_sub_f32_e32 v13, v66, v119
	v_exp_f32_e32 v125, v14
	v_sub_f32_e32 v14, v68, v119
	v_exp_f32_e32 v49, v13
	v_sub_f32_e32 v13, v50, v119
	v_exp_f32_e32 v51, v14
	v_sub_f32_e32 v14, v52, v119
	v_exp_f32_e32 v123, v13
	v_exp_f32_e32 v65, v14
	v_sub_f32_e32 v14, v69, v119
	v_exp_f32_e32 v50, v14
	v_sub_f32_e32 v14, v53, v119
	v_add_f32_e32 v12, v10, v0
	v_exp_f32_e32 v64, v14
	v_add_f32_e32 v12, 0, v12
	v_add_f32_e32 v13, v122, v48
	v_add_f32_e32 v12, v13, v12
	v_add_f32_e32 v13, v123, v49
	v_add_f32_e32 v12, v13, v12
	v_add_f32_e32 v13, v125, v124
	v_add_f32_e32 v14, v13, v12
	v_pk_add_f32 v[12:13], v[64:65], v[50:51]
	v_cvt_pk_bf16_f32 v48, v0, v48
	v_add_f32_e32 v13, v13, v14
	v_add_f32_e32 v14, v12, v13
	v_sub_f32_e32 v12, v70, v119
	v_exp_f32_e32 v53, v12
	v_sub_f32_e32 v12, v54, v119
	v_exp_f32_e32 v67, v12
	v_sub_f32_e32 v12, v71, v119
	v_exp_f32_e32 v52, v12
	v_sub_f32_e32 v12, v55, v119
	v_exp_f32_e32 v66, v12
	v_sub_f32_e32 v12, v72, v119
	v_exp_f32_e32 v69, v12
	v_sub_f32_e32 v12, v56, v119
	v_exp_f32_e32 v71, v12
	v_sub_f32_e32 v12, v73, v119
	v_exp_f32_e32 v68, v12
	v_sub_f32_e32 v12, v57, v119
	v_exp_f32_e32 v70, v12
	v_pk_add_f32 v[12:13], v[66:67], v[52:53]
	v_pk_mov_b32 v[50:51], v[50:51], v[50:51] op_sel:[1,0]
	v_add_f32_e32 v13, v13, v14
	v_add_f32_e32 v126, v12, v13
	v_sub_f32_e32 v12, v74, v119
	v_exp_f32_e32 v73, v12
	v_sub_f32_e32 v12, v58, v119
	v_exp_f32_e32 v121, v12
	v_sub_f32_e32 v12, v75, v119
	v_exp_f32_e32 v72, v12
	v_sub_f32_e32 v12, v59, v119
	v_exp_f32_e32 v120, v12
	v_add_u32_e32 v12, 0x6800, v117
	ds_read2_b64 v[12:15], v12 offset0:128 offset1:130
	v_pk_mov_b32 v[52:53], v[52:53], v[52:53] op_sel:[1,0]
	v_add_u32_e32 v0, 0x7800, v118
	v_cvt_pk_bf16_f32 v50, v50, v51
	v_cvt_pk_bf16_f32 v51, v52, v53
	ds_read2_b64 v[52:55], v0 offset0:192 offset1:194
	v_cvt_pk_bf16_f32 v49, v49, v124
	v_sub_f32_e32 v58, v76, v119
	v_exp_f32_e32 v59, v58
	s_waitcnt lgkmcnt(1)
	v_mfma_f32_32x32x16_bf16 v[32:47], v[12:15], v[48:51], v[32:47]
	v_sub_f32_e32 v12, v77, v119
	v_exp_f32_e32 v58, v12
	v_sub_f32_e32 v12, v78, v119
	v_exp_f32_e32 v75, v12
	v_sub_f32_e32 v12, v79, v119
	v_exp_f32_e32 v74, v12
	v_pk_add_f32 v[56:57], v[70:71], v[68:69]
	s_waitcnt lgkmcnt(0)
	v_mfma_f32_32x32x16_bf16 v[16:31], v[52:55], v[48:51], v[16:31]
	v_pk_mov_b32 v[48:49], v[68:69], v[68:69] op_sel:[1,0]
	v_add_u32_e32 v68, 0x6800, v118
	ds_read2_b64 v[12:15], v68 offset0:132 offset1:134
	v_pk_mov_b32 v[50:51], v[72:73], v[72:73] op_sel:[1,0]
	v_cvt_pk_bf16_f32 v48, v48, v49
	v_cvt_pk_bf16_f32 v49, v50, v51
	v_pk_mov_b32 v[50:51], v[58:59], v[58:59] op_sel:[1,0]
	v_pk_mov_b32 v[52:53], v[74:75], v[74:75] op_sel:[1,0]
	v_cvt_pk_bf16_f32 v50, v50, v51
	v_cvt_pk_bf16_f32 v51, v52, v53
	ds_read2_b64 v[52:55], v0 offset0:196 offset1:198
	s_xor_b64 s[10:11], s[8:9], -1
	s_waitcnt lgkmcnt(1)
	v_mfma_f32_32x32x16_bf16 v[32:47], v[12:15], v[48:51], v[32:47]
	v_add_f32_e32 v12, v57, v126
	v_add_f32_e32 v14, v56, v12
	v_add_f32_e64 v12, v120, v72
	v_add_f32_e64 v13, v121, v73
	v_sub_f32_e32 v56, v60, v119
	v_add_f32_e32 v13, v13, v14
	v_add_f32_e32 v69, v12, v13
	ds_read2_b64 v[12:15], v68 offset0:136 offset1:138
	s_waitcnt lgkmcnt(1)
	v_mfma_f32_32x32x16_bf16 v[16:31], v[52:55], v[48:51], v[16:31]
	v_pk_mov_b32 v[50:51], v[64:65], v[64:65] op_sel:[1,0]
	v_pk_mov_b32 v[52:53], v[66:67], v[66:67] op_sel:[1,0]
	v_cvt_pk_bf16_f32 v50, v50, v51
	v_cvt_pk_bf16_f32 v51, v52, v53
	ds_read2_b64 v[52:55], v0 offset0:200 offset1:202
	v_cvt_pk_bf16_f32 v48, v10, v122
	v_sub_f32_e32 v10, v61, v119
	v_exp_f32_e32 v57, v56
	v_exp_f32_e32 v56, v10
	v_sub_f32_e32 v10, v62, v119
	v_exp_f32_e32 v61, v10
	v_sub_f32_e32 v10, v63, v119
	v_exp_f32_e32 v60, v10
	v_cvt_pk_bf16_f32 v49, v123, v125
	s_mov_b64 s[8:9], 0
	s_andn2_b64 vcc, exec, s[10:11]
	s_waitcnt lgkmcnt(1)
	v_mfma_f32_32x32x16_bf16 v[32:47], v[12:15], v[48:51], v[32:47]
	ds_read2_b64 v[12:15], v68 offset0:140 offset1:142
	s_movk_i32 s2, 0xc0
	s_waitcnt lgkmcnt(1)
	v_mfma_f32_32x32x16_bf16 v[16:31], v[52:55], v[48:51], v[16:31]
	v_pk_mov_b32 v[48:49], v[70:71], v[70:71] op_sel:[1,0]
	v_pk_mov_b32 v[50:51], v[120:121], v[120:121] op_sel:[1,0]
	v_cvt_pk_bf16_f32 v48, v48, v49
	v_cvt_pk_bf16_f32 v49, v50, v51
	v_pk_mov_b32 v[50:51], v[56:57], v[56:57] op_sel:[1,0]
	v_pk_mov_b32 v[52:53], v[60:61], v[60:61] op_sel:[1,0]
	v_cvt_pk_bf16_f32 v50, v50, v51
	v_cvt_pk_bf16_f32 v51, v52, v53
	ds_read2_b64 v[52:55], v0 offset0:204 offset1:206
	s_waitcnt vmcnt(3)
	ds_write_b128 v107, v[2:5]
	s_waitcnt vmcnt(2)
	ds_write_b128 v109, v[6:9] offset:9216
	s_waitcnt lgkmcnt(3)
	v_mfma_f32_32x32x16_bf16 v[32:47], v[12:15], v[48:51], v[32:47]
	v_add_f32_e64 v12, v56, v58
	v_add_f32_e64 v13, v57, v59
	s_waitcnt lgkmcnt(0)
	s_barrier
	v_add_f32_e32 v0, v13, v69
	v_add_f32_e32 v0, v12, v0
	v_pk_add_f32 v[12:13], v[60:61], v[74:75]
	s_waitcnt lgkmcnt(2)
	v_mfma_f32_32x32x16_bf16 v[16:31], v[52:55], v[48:51], v[16:31]
	v_add_f32_e32 v0, v13, v0
	v_add_f32_e32 v0, v12, v0
	v_add_f32_e32 v121, v11, v0
	s_cbranch_vccz .LBB0_266

.LBB0_266:
	s_setprio 0
	v_cmp_lt_i32_e32 vcc, v232, v226
	v_lshlrev_b64 v[2:3], 11, v[138:139]
	s_nop 0
	v_cndmask_b32_e32 v0, v224, v232, vcc
	v_lshlrev_b32_e32 v0, 2, v0
	ds_bpermute_b32 v0, v0, v121
	s_waitcnt lgkmcnt(0)
	v_add_f32_e32 v4, v121, v0
	v_div_scale_f32 v5, s[8:9], v4, v4, 1.0
	v_rcp_f32_e32 v6, v5
	v_readlane_b32 s8, v253, 25
	v_readlane_b32 s9, v253, 26
	v_lshlrev_b32_e32 v0, 1, v106
	s_nop 0
	v_lshl_add_u64 v[2:3], s[8:9], 0, v[2:3]
	v_lshl_add_u64 v[2:3], v[2:3], 0, v[0:1]
	v_fma_f32 v0, -v5, v6, 1.0
	v_fmac_f32_e32 v6, v0, v6
	v_div_scale_f32 v0, vcc, 1.0, v4, 1.0
	v_mul_f32_e32 v7, v0, v6
	v_fma_f32 v8, -v5, v7, v0
	v_fmac_f32_e32 v7, v8, v6
	v_fma_f32 v0, -v5, v7, v0
	v_div_fmas_f32 v0, v0, v6, v7
	v_div_fixup_f32 v4, v0, v4, 1.0
	v_lshlrev_b32_e32 v0, 11, v105
	v_lshl_add_u64 v[2:3], v[2:3], 0, v[0:1]
	v_mov_b32_e32 v105, v1
	v_pk_mul_f32 v[6:7], v[32:33], v[4:5] op_sel_hi:[1,0]
	v_pk_mul_f32 v[8:9], v[34:35], v[4:5] op_sel_hi:[1,0]
	v_lshl_add_u64 v[2:3], v[2:3], 0, v[104:105]
	v_cvt_pk_bf16_f32 v6, v6, v7
	v_cvt_pk_bf16_f32 v7, v8, v9
	global_store_dwordx2 v[2:3], v[6:7], off
	v_pk_mul_f32 v[6:7], v[36:37], v[4:5] op_sel_hi:[1,0]
	v_pk_mul_f32 v[8:9], v[38:39], v[4:5] op_sel_hi:[1,0]
	v_cvt_pk_bf16_f32 v6, v6, v7
	v_cvt_pk_bf16_f32 v7, v8, v9
	global_store_dwordx2 v[2:3], v[6:7], off offset:16
	v_pk_mul_f32 v[6:7], v[40:41], v[4:5] op_sel_hi:[1,0]
	v_pk_mul_f32 v[8:9], v[42:43], v[4:5] op_sel_hi:[1,0]
	v_cvt_pk_bf16_f32 v6, v6, v7
	v_cvt_pk_bf16_f32 v7, v8, v9
	global_store_dwordx2 v[2:3], v[6:7], off offset:32
	v_pk_mul_f32 v[6:7], v[44:45], v[4:5] op_sel_hi:[1,0]
	v_pk_mul_f32 v[8:9], v[46:47], v[4:5] op_sel_hi:[1,0]
	v_cvt_pk_bf16_f32 v6, v6, v7
	v_cvt_pk_bf16_f32 v7, v8, v9
	global_store_dwordx2 v[2:3], v[6:7], off offset:48
	v_pk_mul_f32 v[6:7], v[16:17], v[4:5] op_sel_hi:[1,0]
	v_pk_mul_f32 v[8:9], v[18:19], v[4:5] op_sel_hi:[1,0]
	v_cvt_pk_bf16_f32 v6, v6, v7
	v_cvt_pk_bf16_f32 v7, v8, v9
	global_store_dwordx2 v[2:3], v[6:7], off offset:64
	v_pk_mul_f32 v[6:7], v[20:21], v[4:5] op_sel_hi:[1,0]
	v_pk_mul_f32 v[8:9], v[22:23], v[4:5] op_sel_hi:[1,0]
	v_cvt_pk_bf16_f32 v6, v6, v7
	v_cvt_pk_bf16_f32 v7, v8, v9
	global_store_dwordx2 v[2:3], v[6:7], off offset:80
	v_pk_mul_f32 v[6:7], v[24:25], v[4:5] op_sel_hi:[1,0]
	v_pk_mul_f32 v[8:9], v[26:27], v[4:5] op_sel_hi:[1,0]
	v_cvt_pk_bf16_f32 v6, v6, v7
	v_cvt_pk_bf16_f32 v7, v8, v9
	global_store_dwordx2 v[2:3], v[6:7], off offset:96
	v_pk_mul_f32 v[6:7], v[28:29], v[4:5] op_sel_hi:[1,0]
	v_pk_mul_f32 v[4:5], v[30:31], v[4:5] op_sel_hi:[1,0]
	v_cvt_pk_bf16_f32 v6, v6, v7
	v_cvt_pk_bf16_f32 v7, v4, v5
	global_store_dwordx2 v[2:3], v[6:7], off offset:112
